# cross-half row-max merge off the serial chain in every FoX step and in the differential band steps (rare rescale path keeps it)
# speedup vs baseline: 1.0009x; 1.0009x over previous
.LBB0_492:
	v_pk_add_f32 v[80:81], v[112:113], v[228:229] op_sel_hi:[1,0] neg_lo:[0,1] neg_hi:[0,1]
	v_add_f32_e32 v251, v251, v14
	v_pk_add_f32 v[14:15], v[128:129], v[228:229] op_sel_hi:[1,0] neg_lo:[0,1] neg_hi:[0,1]
	v_pk_add_f32 v[98:99], v[114:115], v[228:229] op_sel_hi:[1,0] neg_lo:[0,1] neg_hi:[0,1]
	v_pk_add_f32 v[82:83], v[130:131], v[228:229] op_sel_hi:[1,0] neg_lo:[0,1] neg_hi:[0,1]
	v_max_f32_e32 v96, v80, v81
	v_pk_add_f32 v[100:101], v[116:117], v[228:229] op_sel_hi:[1,0] neg_lo:[0,1] neg_hi:[0,1]
	v_pk_add_f32 v[102:103], v[118:119], v[228:229] op_sel_hi:[1,0] neg_lo:[0,1] neg_hi:[0,1]
	v_max3_f32 v97, v98, v99, v15
	v_max3_f32 v96, v96, v14, v82
	v_pk_add_f32 v[84:85], v[132:133], v[228:229] op_sel_hi:[1,0] neg_lo:[0,1] neg_hi:[0,1]
	v_pk_add_f32 v[86:87], v[134:135], v[228:229] op_sel_hi:[1,0] neg_lo:[0,1] neg_hi:[0,1]
	v_max3_f32 v96, v96, v83, v100
	v_max3_f32 v97, v97, v102, v103
	v_pk_add_f32 v[104:105], v[120:121], v[228:229] op_sel_hi:[1,0] neg_lo:[0,1] neg_hi:[0,1]
	v_pk_add_f32 v[106:107], v[122:123], v[228:229] op_sel_hi:[1,0] neg_lo:[0,1] neg_hi:[0,1]
	v_max3_f32 v96, v96, v101, v84
	v_max3_f32 v97, v97, v86, v87
	v_pk_add_f32 v[88:89], v[136:137], v[228:229] op_sel_hi:[1,0] neg_lo:[0,1] neg_hi:[0,1]
	v_pk_add_f32 v[90:91], v[138:139], v[228:229] op_sel_hi:[1,0] neg_lo:[0,1] neg_hi:[0,1]
	v_max3_f32 v96, v96, v85, v104
	v_max3_f32 v97, v97, v106, v107
	v_pk_add_f32 v[108:109], v[124:125], v[228:229] op_sel_hi:[1,0] neg_lo:[0,1] neg_hi:[0,1]
	v_pk_add_f32 v[110:111], v[126:127], v[228:229] op_sel_hi:[1,0] neg_lo:[0,1] neg_hi:[0,1]
	v_max3_f32 v96, v96, v105, v88
	v_max3_f32 v97, v97, v90, v91
	v_pk_add_f32 v[92:93], v[140:141], v[228:229] op_sel_hi:[1,0] neg_lo:[0,1] neg_hi:[0,1]
	v_pk_add_f32 v[94:95], v[142:143], v[228:229] op_sel_hi:[1,0] neg_lo:[0,1] neg_hi:[0,1]
	v_max3_f32 v96, v96, v89, v108
	v_max3_f32 v97, v97, v110, v111
	v_max3_f32 v96, v96, v109, v92
	v_max3_f32 v97, v97, v94, v95
	v_max3_f32 v96, v96, v93, v97
	v_cmp_lt_f32_e32 vcc, s83, v96
	s_cmp_lg_u64 vcc, 0
	s_cselect_b64 s[6:7], -1, 0
	s_cbranch_vccnz .LBB0_530

.LBB0_503:
	v_pk_add_f32 v[80:81], v[112:113], v[228:229] op_sel_hi:[1,0] neg_lo:[0,1] neg_hi:[0,1]
	v_add_f32_e32 v251, v251, v14
	v_pk_add_f32 v[14:15], v[128:129], v[228:229] op_sel_hi:[1,0] neg_lo:[0,1] neg_hi:[0,1]
	v_pk_add_f32 v[98:99], v[114:115], v[228:229] op_sel_hi:[1,0] neg_lo:[0,1] neg_hi:[0,1]
	v_pk_add_f32 v[82:83], v[130:131], v[228:229] op_sel_hi:[1,0] neg_lo:[0,1] neg_hi:[0,1]
	v_max_f32_e32 v96, v80, v81
	v_pk_add_f32 v[100:101], v[116:117], v[228:229] op_sel_hi:[1,0] neg_lo:[0,1] neg_hi:[0,1]
	v_pk_add_f32 v[102:103], v[118:119], v[228:229] op_sel_hi:[1,0] neg_lo:[0,1] neg_hi:[0,1]
	v_max3_f32 v97, v98, v99, v15
	v_max3_f32 v96, v96, v14, v82
	v_pk_add_f32 v[84:85], v[132:133], v[228:229] op_sel_hi:[1,0] neg_lo:[0,1] neg_hi:[0,1]
	v_pk_add_f32 v[86:87], v[134:135], v[228:229] op_sel_hi:[1,0] neg_lo:[0,1] neg_hi:[0,1]
	v_max3_f32 v96, v96, v83, v100
	v_max3_f32 v97, v97, v102, v103
	v_pk_add_f32 v[104:105], v[120:121], v[228:229] op_sel_hi:[1,0] neg_lo:[0,1] neg_hi:[0,1]
	v_pk_add_f32 v[106:107], v[122:123], v[228:229] op_sel_hi:[1,0] neg_lo:[0,1] neg_hi:[0,1]
	v_max3_f32 v96, v96, v101, v84
	v_max3_f32 v97, v97, v86, v87
	v_pk_add_f32 v[88:89], v[136:137], v[228:229] op_sel_hi:[1,0] neg_lo:[0,1] neg_hi:[0,1]
	v_pk_add_f32 v[90:91], v[138:139], v[228:229] op_sel_hi:[1,0] neg_lo:[0,1] neg_hi:[0,1]
	v_max3_f32 v96, v96, v85, v104
	v_max3_f32 v97, v97, v106, v107
	v_pk_add_f32 v[108:109], v[124:125], v[228:229] op_sel_hi:[1,0] neg_lo:[0,1] neg_hi:[0,1]
	v_pk_add_f32 v[110:111], v[126:127], v[228:229] op_sel_hi:[1,0] neg_lo:[0,1] neg_hi:[0,1]
	v_max3_f32 v96, v96, v105, v88
	v_max3_f32 v97, v97, v90, v91
	v_pk_add_f32 v[92:93], v[140:141], v[228:229] op_sel_hi:[1,0] neg_lo:[0,1] neg_hi:[0,1]
	v_pk_add_f32 v[94:95], v[142:143], v[228:229] op_sel_hi:[1,0] neg_lo:[0,1] neg_hi:[0,1]
	v_max3_f32 v96, v96, v89, v108
	v_max3_f32 v97, v97, v110, v111
	v_max3_f32 v96, v96, v109, v92
	v_max3_f32 v97, v97, v94, v95
	v_max3_f32 v96, v96, v93, v97
	v_cmp_lt_f32_e32 vcc, s83, v96
	s_cmp_lg_u64 vcc, 0
	s_cselect_b64 s[50:51], -1, 0
	s_cbranch_vccnz .LBB0_533

.LBB0_530:
	v_mov_b32_e32 v97, v96
	s_nop 1
	v_permlane32_swap_b32_e32 v96, v97
	v_max_f32_e32 v97, v97, v97
	v_max_f32_e32 v96, v96, v96
	v_max_f32_e32 v96, v96, v97
	v_max_f32_e32 v96, v96, v96
	v_max_f32_e32 v97, 0, v96
	v_exp_f32_e64 v96, -v97
	s_and_saveexec_b64 s[46:47], s[4:5]
	ds_write_b32 v243, v96
	s_or_b64 exec, exec, s[46:47]
	v_sub_f32_e32 v80, v80, v97
	v_sub_f32_e32 v81, v81, v97
	v_sub_f32_e32 v98, v98, v97
	v_sub_f32_e32 v99, v99, v97
	v_sub_f32_e32 v100, v100, v97
	v_sub_f32_e32 v101, v101, v97
	v_sub_f32_e32 v102, v102, v97
	v_sub_f32_e32 v103, v103, v97
	v_sub_f32_e32 v104, v104, v97
	v_sub_f32_e32 v105, v105, v97
	v_sub_f32_e32 v106, v106, v97
	v_sub_f32_e32 v107, v107, v97
	v_sub_f32_e32 v108, v108, v97
	v_sub_f32_e32 v109, v109, v97
	v_sub_f32_e32 v110, v110, v97
	v_sub_f32_e32 v111, v111, v97
	v_sub_f32_e32 v14, v14, v97
	v_sub_f32_e32 v15, v15, v97
	v_sub_f32_e32 v82, v82, v97
	v_sub_f32_e32 v83, v83, v97
	v_sub_f32_e32 v84, v84, v97
	v_sub_f32_e32 v85, v85, v97
	v_sub_f32_e32 v86, v86, v97
	v_sub_f32_e32 v87, v87, v97
	v_sub_f32_e32 v88, v88, v97
	v_sub_f32_e32 v89, v89, v97
	v_sub_f32_e32 v90, v90, v97
	v_sub_f32_e32 v91, v91, v97
	v_sub_f32_e32 v92, v92, v97
	v_sub_f32_e32 v93, v93, v97
	v_sub_f32_e32 v94, v94, v97
	v_sub_f32_e32 v95, v95, v97
	v_add_f32_e32 v228, v228, v97
	v_mul_f32_e32 v251, v251, v96
	s_branch .LBB0_493
.LBB0_533:
	v_mov_b32_e32 v97, v96
	s_nop 1
	v_permlane32_swap_b32_e32 v96, v97
	v_max_f32_e32 v97, v97, v97
	v_max_f32_e32 v96, v96, v96
	v_max_f32_e32 v96, v96, v97
	v_max_f32_e32 v96, v96, v96
	v_max_f32_e32 v97, 0, v96
	v_exp_f32_e64 v96, -v97
	s_and_saveexec_b64 s[6:7], s[4:5]
	ds_write_b32 v243, v96
	s_or_b64 exec, exec, s[6:7]
	v_sub_f32_e32 v80, v80, v97
	v_sub_f32_e32 v81, v81, v97
	v_sub_f32_e32 v98, v98, v97
	v_sub_f32_e32 v99, v99, v97
	v_sub_f32_e32 v100, v100, v97
	v_sub_f32_e32 v101, v101, v97
	v_sub_f32_e32 v102, v102, v97
	v_sub_f32_e32 v103, v103, v97
	v_sub_f32_e32 v104, v104, v97
	v_sub_f32_e32 v105, v105, v97
	v_sub_f32_e32 v106, v106, v97
	v_sub_f32_e32 v107, v107, v97
	v_sub_f32_e32 v108, v108, v97
	v_sub_f32_e32 v109, v109, v97
	v_sub_f32_e32 v110, v110, v97
	v_sub_f32_e32 v111, v111, v97
	v_sub_f32_e32 v14, v14, v97
	v_sub_f32_e32 v15, v15, v97
	v_sub_f32_e32 v82, v82, v97
	v_sub_f32_e32 v83, v83, v97
	v_sub_f32_e32 v84, v84, v97
	v_sub_f32_e32 v85, v85, v97
	v_sub_f32_e32 v86, v86, v97
	v_sub_f32_e32 v87, v87, v97
	v_sub_f32_e32 v88, v88, v97
	v_sub_f32_e32 v89, v89, v97
	v_sub_f32_e32 v90, v90, v97
	v_sub_f32_e32 v91, v91, v97
	v_sub_f32_e32 v92, v92, v97
	v_sub_f32_e32 v93, v93, v97
	v_sub_f32_e32 v94, v94, v97
	v_sub_f32_e32 v95, v95, v97
	v_add_f32_e32 v228, v228, v97
	v_mul_f32_e32 v251, v251, v96
	s_branch .LBB0_504
.LBB0_536:
	v_add_u32_e32 v0, s93, v250
	ds_read_b64_tr_b16 v[2:3], v0 offset:24576
	ds_read_b64_tr_b16 v[4:5], v0 offset:25088
	s_waitcnt lgkmcnt(9)
	v_mfma_f32_32x32x16_bf16 v[112:127], v[204:207], v[172:175], 0
	v_add_f32_e32 v6, v96, v97
	v_add_f32_e32 v6, v98, v6
	v_add_f32_e32 v6, v99, v6
	v_add_f32_e32 v6, v100, v6
	v_add_f32_e32 v10, v101, v6
	v_cvt_pk_bf16_f32 v156, v96, v97
	v_cvt_pk_bf16_f32 v157, v98, v99
	ds_read_b64_tr_b16 v[6:7], v0 offset:28672
	ds_read_b64_tr_b16 v[8:9], v0 offset:29184
	v_add_f32_e32 v10, v102, v10
	v_add_f32_e32 v10, v103, v10
	v_add_f32_e32 v10, v104, v10
	v_add_f32_e32 v14, v105, v10
	v_cvt_pk_bf16_f32 v158, v100, v101
	v_cvt_pk_bf16_f32 v159, v102, v103
	s_waitcnt lgkmcnt(10)
	v_mfma_f32_32x32x16_bf16 v[128:143], v[200:203], v[172:175], 0
	ds_read_b64_tr_b16 v[10:11], v0 offset:25600
	ds_read_b64_tr_b16 v[12:13], v0 offset:26112
	s_waitcnt lgkmcnt(11)
	v_mfma_f32_32x32x16_bf16 v[112:127], v[196:199], v[168:171], v[112:127]
	v_add_f32_e32 v14, v106, v14
	v_add_f32_e32 v14, v107, v14
	v_add_f32_e32 v14, v108, v14
	v_add_f32_e32 v14, v109, v14
	v_cvt_pk_bf16_f32 v152, v104, v105
	v_cvt_pk_bf16_f32 v153, v106, v107
	ds_read_b64_tr_b16 v[172:173], v0 offset:29696
	ds_read_b64_tr_b16 v[174:175], v0 offset:30208
	v_add_f32_e32 v14, v110, v14
	v_add_f32_e32 v14, v111, v14
	v_add_f32_e32 v14, v80, v14
	v_add_f32_e32 v14, v81, v14
	v_cvt_pk_bf16_f32 v154, v108, v109
	v_cvt_pk_bf16_f32 v155, v110, v111
	s_waitcnt lgkmcnt(12)
	v_mfma_f32_32x32x16_bf16 v[128:143], v[192:195], v[168:171], v[128:143]
	ds_read_b64_tr_b16 v[168:169], v0 offset:26624
	ds_read_b64_tr_b16 v[170:171], v0 offset:27136
	s_waitcnt lgkmcnt(13)
	v_mfma_f32_32x32x16_bf16 v[112:127], v[188:191], v[164:167], v[112:127]
	v_add_f32_e32 v14, v82, v14
	v_add_f32_e32 v14, v83, v14
	v_add_f32_e32 v14, v84, v14
	v_add_f32_e32 v14, v85, v14
	v_cvt_pk_bf16_f32 v148, v80, v81
	v_cvt_pk_bf16_f32 v149, v82, v83
	ds_read_b64_tr_b16 v[188:189], v0 offset:30720
	ds_read_b64_tr_b16 v[190:191], v0 offset:31232
	v_add_f32_e32 v14, v86, v14
	v_add_f32_e32 v14, v87, v14
	v_add_f32_e32 v14, v88, v14
	v_add_f32_e32 v14, v89, v14
	v_cvt_pk_bf16_f32 v150, v84, v85
	v_cvt_pk_bf16_f32 v151, v86, v87
	s_waitcnt lgkmcnt(14)
	v_mfma_f32_32x32x16_bf16 v[128:143], v[184:187], v[164:167], v[128:143]
	ds_read_b64_tr_b16 v[164:165], v0 offset:27648
	ds_read_b64_tr_b16 v[166:167], v0 offset:28160
	s_waitcnt lgkmcnt(14)
; __device__ __forceinline__ void biasd(f32x16&p0,f32x16&p1,const __attribute__((address_space(3))) float*lut,int base){
;   #pragma unroll
;   for(int r=0;r<16;++r){ const int d0=base-((r&3)+8*(r>>2)); unsigned i0=(unsigned)d0; i0=i0>127u?127u:i0; unsigned i1=(unsigned)(d0-32); i1=i1>127u?127u:i1; p0[r]+=lut[i0]; p1[r]+=lut[i1];
;     if((r&3)==3){ asm volatile("":"+v"(p0),"+v"(p1)); __builtin_amdgcn_sched_barrier(0); } }
; }
	v_mfma_f32_32x32x16_bf16 v[112:127], v[180:183], v[160:163], v[112:127]
	v_add_f32_e32 v14, v90, v14
	v_add_f32_e32 v14, v91, v14
	v_add_f32_e32 v14, v92, v14
	v_add_f32_e32 v14, v93, v14
	v_cvt_pk_bf16_f32 v144, v88, v89
	v_cvt_pk_bf16_f32 v145, v90, v91
	ds_read_b64_tr_b16 v[180:181], v0 offset:31744
	ds_read_b64_tr_b16 v[182:183], v0 offset:32256
	v_add_f32_e32 v14, v94, v14
	v_add_f32_e32 v14, v95, v14
	v_add_f32_e32 v96, 0, v14
	v_cvt_pk_bf16_f32 v146, v92, v93
	v_cvt_pk_bf16_f32 v147, v94, v95
	v_mfma_f32_32x32x16_bf16 v[128:143], v[176:179], v[160:163], v[128:143]
	v_sub_u32_e32 v86, v246, v245
	v_add_u32_e32 v80, 0xffffff3f, v86
	v_min_u32_e32 v80, 0x7f, v80
	v_lshl_add_u32 v82, v80, 2, s89
	v_add_u32_e32 v80, 0xffffff3e, v86
	v_add_u32_e32 v14, 0xffffff40, v86
	v_add_u32_e32 v15, 0xffffff20, v86
	v_add_u32_e32 v81, 0xffffff1f, v86
	v_min_u32_e32 v80, 0x7f, v80
	v_add_u32_e32 v83, 0xffffff1e, v86
	v_add_u32_e32 v85, 0xffffff1d, v86
	v_min_u32_e32 v14, 0x7f, v14
	v_min_u32_e32 v15, 0x7f, v15
	v_min_u32_e32 v81, 0x7f, v81
	v_min_u32_e32 v83, 0x7f, v83
	v_lshl_add_u32 v84, v80, 2, s89
	v_add_u32_e32 v80, 0xffffff3d, v86
	v_min_u32_e32 v85, 0x7f, v85
	v_lshl_add_u32 v14, v14, 2, s89
	v_lshl_add_u32 v15, v15, 2, s89
	v_lshl_add_u32 v81, v81, 2, s89
	v_lshl_add_u32 v83, v83, 2, s89
	v_min_u32_e32 v80, 0x7f, v80
	v_lshl_add_u32 v85, v85, 2, s89
	v_lshl_add_u32 v87, v80, 2, s89
	ds_read_b32 v14, v14
	ds_read_b32 v80, v15
	ds_read_b32 v15, v82
	ds_read_b32 v81, v81
	ds_read_b32 v82, v84
	ds_read_b32 v84, v83
	ds_read_b32 v83, v87
	ds_read_b32 v85, v85
	s_waitcnt lgkmcnt(5)
	v_pk_add_f32 v[112:113], v[112:113], v[14:15]
	s_waitcnt lgkmcnt(4)
	v_pk_add_f32 v[128:129], v[128:129], v[80:81]
	s_waitcnt lgkmcnt(1)
	v_pk_add_f32 v[114:115], v[114:115], v[82:83]
	s_waitcnt lgkmcnt(0)
	v_pk_add_f32 v[130:131], v[130:131], v[84:85]
	s_nop 0
	v_add_u32_e32 v80, 0xffffff37, v86
	v_min_u32_e32 v80, 0x7f, v80
	v_lshl_add_u32 v82, v80, 2, s89
	v_add_u32_e32 v80, 0xffffff36, v86
	v_add_u32_e32 v14, 0xffffff38, v86
	v_add_u32_e32 v15, 0xffffff18, v86
	v_add_u32_e32 v81, 0xffffff17, v86
	v_min_u32_e32 v80, 0x7f, v80
	v_add_u32_e32 v83, 0xffffff16, v86
	v_add_u32_e32 v85, 0xffffff15, v86
	v_min_u32_e32 v14, 0x7f, v14
	v_min_u32_e32 v15, 0x7f, v15
	v_min_u32_e32 v81, 0x7f, v81
	v_min_u32_e32 v83, 0x7f, v83
	v_lshl_add_u32 v84, v80, 2, s89
	v_add_u32_e32 v80, 0xffffff35, v86
	v_min_u32_e32 v85, 0x7f, v85
	v_lshl_add_u32 v14, v14, 2, s89
	v_lshl_add_u32 v15, v15, 2, s89
	v_lshl_add_u32 v81, v81, 2, s89
	v_lshl_add_u32 v83, v83, 2, s89
	v_min_u32_e32 v80, 0x7f, v80
	v_lshl_add_u32 v85, v85, 2, s89
	v_lshl_add_u32 v87, v80, 2, s89
	ds_read_b32 v14, v14
	ds_read_b32 v80, v15
	ds_read_b32 v15, v82
	ds_read_b32 v81, v81
	ds_read_b32 v82, v84
	ds_read_b32 v84, v83
	ds_read_b32 v83, v87
	ds_read_b32 v85, v85
	s_waitcnt lgkmcnt(5)
	v_pk_add_f32 v[116:117], v[14:15], v[116:117]
	s_waitcnt lgkmcnt(4)
	v_pk_add_f32 v[132:133], v[132:133], v[80:81]
	s_waitcnt lgkmcnt(1)
	v_pk_add_f32 v[118:119], v[118:119], v[82:83]
	s_waitcnt lgkmcnt(0)
	v_pk_add_f32 v[134:135], v[134:135], v[84:85]
	s_nop 0
	v_add_u32_e32 v80, 0xffffff2f, v86
	v_min_u32_e32 v80, 0x7f, v80
	v_lshl_add_u32 v82, v80, 2, s89
	v_add_u32_e32 v80, 0xffffff2e, v86
	v_add_u32_e32 v14, 0xffffff30, v86
	v_add_u32_e32 v15, 0xffffff10, v86
	v_add_u32_e32 v81, 0xffffff0f, v86
	v_min_u32_e32 v80, 0x7f, v80
	v_add_u32_e32 v83, 0xffffff0e, v86
	v_add_u32_e32 v85, 0xffffff0d, v86
	v_min_u32_e32 v14, 0x7f, v14
	v_min_u32_e32 v15, 0x7f, v15
	v_min_u32_e32 v81, 0x7f, v81
	v_min_u32_e32 v83, 0x7f, v83
	v_lshl_add_u32 v84, v80, 2, s89
	v_add_u32_e32 v80, 0xffffff2d, v86
	v_min_u32_e32 v85, 0x7f, v85
	v_lshl_add_u32 v14, v14, 2, s89
	v_lshl_add_u32 v15, v15, 2, s89
	v_lshl_add_u32 v81, v81, 2, s89
	v_lshl_add_u32 v83, v83, 2, s89
	v_min_u32_e32 v80, 0x7f, v80
	v_lshl_add_u32 v85, v85, 2, s89
	v_lshl_add_u32 v87, v80, 2, s89
	ds_read_b32 v14, v14
	ds_read_b32 v80, v15
	ds_read_b32 v15, v82
	ds_read_b32 v81, v81
	ds_read_b32 v82, v84
	ds_read_b32 v84, v83
	ds_read_b32 v83, v87
	ds_read_b32 v85, v85
	s_waitcnt lgkmcnt(5)
	v_pk_add_f32 v[120:121], v[14:15], v[120:121]
	s_waitcnt lgkmcnt(4)
	v_pk_add_f32 v[136:137], v[136:137], v[80:81]
	s_waitcnt lgkmcnt(1)
	v_pk_add_f32 v[122:123], v[122:123], v[82:83]
	s_waitcnt lgkmcnt(0)
	v_pk_add_f32 v[138:139], v[138:139], v[84:85]
	s_nop 0
	v_add_u32_e32 v80, 0xffffff27, v86
	v_min_u32_e32 v80, 0x7f, v80
	v_lshl_add_u32 v82, v80, 2, s89
	v_add_u32_e32 v80, 0xffffff26, v86
	v_add_u32_e32 v14, 0xffffff28, v86
	v_add_u32_e32 v15, 0xffffff08, v86
	v_add_u32_e32 v81, 0xffffff07, v86
	v_min_u32_e32 v80, 0x7f, v80
	v_add_u32_e32 v83, 0xffffff06, v86
	v_add_u32_e32 v85, 0xffffff05, v86
	v_min_u32_e32 v14, 0x7f, v14
	v_min_u32_e32 v15, 0x7f, v15
	v_min_u32_e32 v81, 0x7f, v81
	v_min_u32_e32 v83, 0x7f, v83
	v_lshl_add_u32 v84, v80, 2, s89
	v_add_u32_e32 v80, 0xffffff25, v86
	v_min_u32_e32 v85, 0x7f, v85
	v_lshl_add_u32 v14, v14, 2, s89
	v_lshl_add_u32 v15, v15, 2, s89
	v_lshl_add_u32 v81, v81, 2, s89
	v_lshl_add_u32 v83, v83, 2, s89
	v_min_u32_e32 v80, 0x7f, v80
	v_lshl_add_u32 v85, v85, 2, s89
	v_lshl_add_u32 v86, v80, 2, s89
	ds_read_b32 v14, v14
	ds_read_b32 v80, v15
	ds_read_b32 v15, v82
	ds_read_b32 v81, v81
	ds_read_b32 v82, v84
	ds_read_b32 v84, v83
	ds_read_b32 v83, v86
	ds_read_b32 v85, v85
	s_waitcnt lgkmcnt(5)
	v_pk_add_f32 v[124:125], v[14:15], v[124:125]
	s_waitcnt lgkmcnt(4)
	v_pk_add_f32 v[140:141], v[140:141], v[80:81]
	s_waitcnt lgkmcnt(1)
	v_pk_add_f32 v[126:127], v[126:127], v[82:83]
	s_waitcnt lgkmcnt(0)
; __device__ __forceinline__ void cmask(f32x16&p0,f32x16&p1,int jb,int qrel,int hi){
;   const float NEG=-INFINITY; int kb=64*jb+4*hi;
;   #pragma unroll
;   for(int r=0;r<16;++r){int kv=kb+(r&3)+8*(r>>2); if(kv>qrel)p0[r]=NEG; if(kv+32>qrel)p1[r]=NEG;}
; }
	v_pk_add_f32 v[142:143], v[142:143], v[84:85]
	s_nop 0
	v_or_b32_e32 v14, 0xe0, v245
	v_or_b32_e32 v15, 0xc0, v245
	v_cmp_le_u32_e32 vcc, v14, v246
	v_or_b32_e32 v82, 0xc2, v245
	v_or_b32_e32 v83, 0xe2, v245
	v_cndmask_b32_e32 v14, v235, v128, vcc
	v_cmp_lt_u32_e32 vcc, v15, v246
	v_or_b32_e32 v85, 0xe3, v245
	v_or_b32_e32 v86, 0xc8, v245
	v_cndmask_b32_e32 v81, v235, v113, vcc
	v_cmp_le_u32_e32 vcc, v15, v246
	v_or_b32_e32 v15, 0xe1, v245
	v_or_b32_e32 v87, 0xe8, v245
	v_cndmask_b32_e32 v80, v235, v112, vcc
	v_cmp_le_u32_e32 vcc, v15, v246
	v_or_b32_e32 v89, 0xe9, v245
	v_or_b32_e32 v90, 0xca, v245
	v_cndmask_b32_e32 v15, v235, v129, vcc
	v_cmp_le_u32_e32 vcc, v82, v246
	v_or_b32_e32 v91, 0xea, v245
	v_or_b32_e32 v93, 0xeb, v245
	v_cndmask_b32_e32 v82, v235, v114, vcc
	v_cmp_le_u32_e32 vcc, v83, v246
	v_or_b32_e32 v83, 0xc3, v245
	v_or_b32_e32 v94, 0xd0, v245
	v_cndmask_b32_e32 v84, v235, v130, vcc
	v_cmp_le_u32_e32 vcc, v83, v246
	v_or_b32_e32 v95, 0xf0, v245
	v_or_b32_e32 v97, 0xf1, v245
	v_cndmask_b32_e32 v83, v235, v115, vcc
	v_cmp_le_u32_e32 vcc, v85, v246
	v_pk_add_f32 v[80:81], v[80:81], v[228:229] op_sel_hi:[1,0] neg_lo:[0,1] neg_hi:[0,1]
	v_pk_add_f32 v[14:15], v[14:15], v[228:229] op_sel_hi:[1,0] neg_lo:[0,1] neg_hi:[0,1]
	v_cndmask_b32_e32 v85, v235, v131, vcc
	v_cmp_le_u32_e32 vcc, v86, v246
	v_pk_add_f32 v[98:99], v[82:83], v[228:229] op_sel_hi:[1,0] neg_lo:[0,1] neg_hi:[0,1]
	v_pk_add_f32 v[82:83], v[84:85], v[228:229] op_sel_hi:[1,0] neg_lo:[0,1] neg_hi:[0,1]
	v_cndmask_b32_e32 v86, v235, v116, vcc
	v_cmp_le_u32_e32 vcc, v87, v246
	v_or_b32_e32 v87, 0xc9, v245
	s_nop 0
	v_cndmask_b32_e32 v88, v235, v132, vcc
	v_cmp_le_u32_e32 vcc, v87, v246
	s_nop 1
	v_cndmask_b32_e32 v87, v235, v117, vcc
	v_cmp_le_u32_e32 vcc, v89, v246
	v_pk_add_f32 v[100:101], v[86:87], v[228:229] op_sel_hi:[1,0] neg_lo:[0,1] neg_hi:[0,1]
	s_nop 0
	v_cndmask_b32_e32 v89, v235, v133, vcc
	v_cmp_le_u32_e32 vcc, v90, v246
	v_pk_add_f32 v[84:85], v[88:89], v[228:229] op_sel_hi:[1,0] neg_lo:[0,1] neg_hi:[0,1]
	s_nop 0
	v_cndmask_b32_e32 v90, v235, v118, vcc
	v_cmp_le_u32_e32 vcc, v91, v246
	v_or_b32_e32 v91, 0xcb, v245
	s_nop 0
	v_cndmask_b32_e32 v92, v235, v134, vcc
	v_cmp_le_u32_e32 vcc, v91, v246
	s_nop 1
	v_cndmask_b32_e32 v91, v235, v119, vcc
	v_cmp_le_u32_e32 vcc, v93, v246
	v_pk_add_f32 v[102:103], v[90:91], v[228:229] op_sel_hi:[1,0] neg_lo:[0,1] neg_hi:[0,1]
	s_nop 0
	v_cndmask_b32_e32 v93, v235, v135, vcc
	v_cmp_le_u32_e32 vcc, v94, v246
	v_pk_add_f32 v[86:87], v[92:93], v[228:229] op_sel_hi:[1,0] neg_lo:[0,1] neg_hi:[0,1]
	s_nop 0
	v_cndmask_b32_e32 v94, v235, v120, vcc
	v_cmp_le_u32_e32 vcc, v95, v246
	v_or_b32_e32 v95, 0xd1, v245
	s_nop 0
	v_cndmask_b32_e32 v106, v235, v136, vcc
	v_cmp_le_u32_e32 vcc, v95, v246
	s_nop 1
	v_cndmask_b32_e32 v95, v235, v121, vcc
	v_cmp_le_u32_e32 vcc, v97, v246
	v_or_b32_e32 v97, 0xd2, v245
	v_pk_add_f32 v[104:105], v[94:95], v[228:229] op_sel_hi:[1,0] neg_lo:[0,1] neg_hi:[0,1]
	v_cndmask_b32_e32 v107, v235, v137, vcc
	v_cmp_le_u32_e32 vcc, v97, v246
	v_or_b32_e32 v97, 0xf2, v245
	v_pk_add_f32 v[88:89], v[106:107], v[228:229] op_sel_hi:[1,0] neg_lo:[0,1] neg_hi:[0,1]
	v_cndmask_b32_e32 v108, v235, v122, vcc
	v_cmp_le_u32_e32 vcc, v97, v246
	v_or_b32_e32 v97, 0xd3, v245
	s_nop 0
	v_cndmask_b32_e32 v110, v235, v138, vcc
	v_cmp_le_u32_e32 vcc, v97, v246
	v_or_b32_e32 v97, 0xf3, v245
	s_nop 0
	v_cndmask_b32_e32 v109, v235, v123, vcc
	v_cmp_le_u32_e32 vcc, v97, v246
	v_or_b32_e32 v97, 0xd8, v245
	v_pk_add_f32 v[106:107], v[108:109], v[228:229] op_sel_hi:[1,0] neg_lo:[0,1] neg_hi:[0,1]
	v_cndmask_b32_e32 v111, v235, v139, vcc
	v_cmp_le_u32_e32 vcc, v97, v246
	v_or_b32_e32 v97, 0xf8, v245
	v_pk_add_f32 v[90:91], v[110:111], v[228:229] op_sel_hi:[1,0] neg_lo:[0,1] neg_hi:[0,1]
	v_cndmask_b32_e32 v112, v235, v124, vcc
	v_cmp_le_u32_e32 vcc, v97, v246
	v_or_b32_e32 v97, 0xd9, v245
	s_nop 0
	v_cndmask_b32_e32 v114, v235, v140, vcc
	v_cmp_le_u32_e32 vcc, v97, v246
	v_or_b32_e32 v97, 0xf9, v245
	s_nop 0
	v_cndmask_b32_e32 v113, v235, v125, vcc
	v_cmp_le_u32_e32 vcc, v97, v246
	v_or_b32_e32 v97, 0xda, v245
	v_pk_add_f32 v[108:109], v[112:113], v[228:229] op_sel_hi:[1,0] neg_lo:[0,1] neg_hi:[0,1]
	v_cndmask_b32_e32 v115, v235, v141, vcc
	v_cmp_le_u32_e32 vcc, v97, v246
	v_or_b32_e32 v97, 0xfa, v245
	v_max3_f32 v112, v98, v99, v15
	v_cndmask_b32_e32 v116, v235, v126, vcc
	v_cmp_le_u32_e32 vcc, v97, v246
	v_or_b32_e32 v97, 0xdb, v245
	v_max3_f32 v112, v112, v102, v103
	v_cndmask_b32_e32 v118, v235, v142, vcc
	v_cmp_le_u32_e32 vcc, v97, v246
	v_or_b32_e32 v97, 0xfb, v245
	v_max3_f32 v112, v112, v86, v87
	v_cndmask_b32_e32 v117, v235, v127, vcc
	v_cmp_le_u32_e32 vcc, v97, v246
	v_max_f32_e32 v97, v80, v81
	v_max3_f32 v97, v97, v14, v82
	v_max3_f32 v97, v97, v83, v100
	v_max3_f32 v97, v97, v101, v84
	v_max3_f32 v97, v97, v85, v104
	v_max3_f32 v112, v112, v106, v107
	v_cndmask_b32_e32 v119, v235, v143, vcc
	v_pk_add_f32 v[110:111], v[116:117], v[228:229] op_sel_hi:[1,0] neg_lo:[0,1] neg_hi:[0,1]
	v_max3_f32 v97, v97, v105, v88
	v_max3_f32 v112, v112, v90, v91
	v_pk_add_f32 v[92:93], v[114:115], v[228:229] op_sel_hi:[1,0] neg_lo:[0,1] neg_hi:[0,1]
	v_pk_add_f32 v[94:95], v[118:119], v[228:229] op_sel_hi:[1,0] neg_lo:[0,1] neg_hi:[0,1]
	v_max3_f32 v97, v97, v89, v108
	v_max3_f32 v112, v112, v110, v111
	v_max3_f32 v97, v97, v109, v92
	v_max3_f32 v113, v112, v94, v95
	v_add_f32_e32 v112, v251, v96
	v_max3_f32 v96, v97, v93, v113
	v_cmp_lt_f32_e32 vcc, s83, v96
	s_cmp_lg_u64 vcc, 0
	s_cselect_b64 s[4:5], -1, 0
	s_cbranch_vccnz .LBB0_541

.LBB0_541:
	v_mov_b32_e32 v97, v96
	s_nop 1
	v_permlane32_swap_b32_e32 v96, v97
	v_max_f32_e32 v97, v97, v97
	v_max_f32_e32 v96, v96, v96
	v_max_f32_e32 v96, v96, v97
	v_max_f32_e32 v96, v96, v96
	v_max_f32_e32 v97, 0, v96
	v_exp_f32_e64 v96, -v97
	v_cmp_gt_u32_e32 vcc, 32, v237
	s_and_saveexec_b64 s[6:7], vcc
	ds_write_b32 v243, v96
	s_or_b64 exec, exec, s[6:7]
	v_sub_f32_e32 v80, v80, v97
	v_sub_f32_e32 v81, v81, v97
	v_sub_f32_e32 v98, v98, v97
	v_sub_f32_e32 v99, v99, v97
	v_sub_f32_e32 v100, v100, v97
	v_sub_f32_e32 v101, v101, v97
	v_sub_f32_e32 v102, v102, v97
	v_sub_f32_e32 v103, v103, v97
	v_sub_f32_e32 v104, v104, v97
	v_sub_f32_e32 v105, v105, v97
	v_sub_f32_e32 v106, v106, v97
	v_sub_f32_e32 v107, v107, v97
	v_sub_f32_e32 v108, v108, v97
	v_sub_f32_e32 v109, v109, v97
	v_sub_f32_e32 v110, v110, v97
	v_sub_f32_e32 v111, v111, v97
	v_sub_f32_e32 v14, v14, v97
	v_sub_f32_e32 v15, v15, v97
	v_sub_f32_e32 v82, v82, v97
	v_sub_f32_e32 v83, v83, v97
	v_sub_f32_e32 v84, v84, v97
	v_sub_f32_e32 v85, v85, v97
	v_sub_f32_e32 v86, v86, v97
	v_sub_f32_e32 v87, v87, v97
	v_sub_f32_e32 v88, v88, v97
	v_sub_f32_e32 v89, v89, v97
	v_sub_f32_e32 v90, v90, v97
	v_sub_f32_e32 v91, v91, v97
	v_sub_f32_e32 v92, v92, v97
	v_sub_f32_e32 v93, v93, v97
	v_sub_f32_e32 v94, v94, v97
	v_sub_f32_e32 v95, v95, v97
	v_mul_f32_e32 v112, v112, v96
	s_branch .LBB0_537

.LBB0_1532:
	v_pk_add_f32 v[80:81], v[112:113], v[228:229] op_sel_hi:[1,0] neg_lo:[0,1] neg_hi:[0,1]
	v_add_f32_e32 v250, v250, v14
	v_pk_add_f32 v[14:15], v[128:129], v[228:229] op_sel_hi:[1,0] neg_lo:[0,1] neg_hi:[0,1]
	v_pk_add_f32 v[98:99], v[114:115], v[228:229] op_sel_hi:[1,0] neg_lo:[0,1] neg_hi:[0,1]
	v_pk_add_f32 v[82:83], v[130:131], v[228:229] op_sel_hi:[1,0] neg_lo:[0,1] neg_hi:[0,1]
	v_max_f32_e32 v96, v80, v81
	v_pk_add_f32 v[100:101], v[116:117], v[228:229] op_sel_hi:[1,0] neg_lo:[0,1] neg_hi:[0,1]
	v_pk_add_f32 v[102:103], v[118:119], v[228:229] op_sel_hi:[1,0] neg_lo:[0,1] neg_hi:[0,1]
	v_max3_f32 v97, v98, v99, v15
	v_max3_f32 v96, v96, v14, v82
	v_pk_add_f32 v[84:85], v[132:133], v[228:229] op_sel_hi:[1,0] neg_lo:[0,1] neg_hi:[0,1]
	v_pk_add_f32 v[86:87], v[134:135], v[228:229] op_sel_hi:[1,0] neg_lo:[0,1] neg_hi:[0,1]
	v_max3_f32 v96, v96, v83, v100
	v_max3_f32 v97, v97, v102, v103
	v_pk_add_f32 v[104:105], v[120:121], v[228:229] op_sel_hi:[1,0] neg_lo:[0,1] neg_hi:[0,1]
	v_pk_add_f32 v[106:107], v[122:123], v[228:229] op_sel_hi:[1,0] neg_lo:[0,1] neg_hi:[0,1]
	v_max3_f32 v96, v96, v101, v84
	v_max3_f32 v97, v97, v86, v87
	v_pk_add_f32 v[88:89], v[136:137], v[228:229] op_sel_hi:[1,0] neg_lo:[0,1] neg_hi:[0,1]
	v_pk_add_f32 v[90:91], v[138:139], v[228:229] op_sel_hi:[1,0] neg_lo:[0,1] neg_hi:[0,1]
	v_max3_f32 v96, v96, v85, v104
	v_max3_f32 v97, v97, v106, v107
	v_pk_add_f32 v[108:109], v[124:125], v[228:229] op_sel_hi:[1,0] neg_lo:[0,1] neg_hi:[0,1]
	v_pk_add_f32 v[110:111], v[126:127], v[228:229] op_sel_hi:[1,0] neg_lo:[0,1] neg_hi:[0,1]
	v_max3_f32 v96, v96, v105, v88
	v_max3_f32 v97, v97, v90, v91
	v_pk_add_f32 v[92:93], v[140:141], v[228:229] op_sel_hi:[1,0] neg_lo:[0,1] neg_hi:[0,1]
	v_pk_add_f32 v[94:95], v[142:143], v[228:229] op_sel_hi:[1,0] neg_lo:[0,1] neg_hi:[0,1]
	v_max3_f32 v96, v96, v89, v108
	v_max3_f32 v97, v97, v110, v111
	v_max3_f32 v96, v96, v109, v92
	v_max3_f32 v97, v97, v94, v95
	v_max3_f32 v96, v96, v93, v97
	v_cmp_lt_f32_e32 vcc, s78, v96
	s_cmp_lg_u64 vcc, 0
	s_cselect_b64 s[10:11], -1, 0
	s_cbranch_vccnz .LBB0_1570

.LBB0_1543:
	v_pk_add_f32 v[80:81], v[112:113], v[228:229] op_sel_hi:[1,0] neg_lo:[0,1] neg_hi:[0,1]
	v_add_f32_e32 v250, v250, v14
	v_pk_add_f32 v[14:15], v[128:129], v[228:229] op_sel_hi:[1,0] neg_lo:[0,1] neg_hi:[0,1]
	v_pk_add_f32 v[98:99], v[114:115], v[228:229] op_sel_hi:[1,0] neg_lo:[0,1] neg_hi:[0,1]
	v_pk_add_f32 v[82:83], v[130:131], v[228:229] op_sel_hi:[1,0] neg_lo:[0,1] neg_hi:[0,1]
	v_max_f32_e32 v96, v80, v81
	v_pk_add_f32 v[100:101], v[116:117], v[228:229] op_sel_hi:[1,0] neg_lo:[0,1] neg_hi:[0,1]
	v_pk_add_f32 v[102:103], v[118:119], v[228:229] op_sel_hi:[1,0] neg_lo:[0,1] neg_hi:[0,1]
	v_max3_f32 v97, v98, v99, v15
	v_max3_f32 v96, v96, v14, v82
	v_pk_add_f32 v[84:85], v[132:133], v[228:229] op_sel_hi:[1,0] neg_lo:[0,1] neg_hi:[0,1]
	v_pk_add_f32 v[86:87], v[134:135], v[228:229] op_sel_hi:[1,0] neg_lo:[0,1] neg_hi:[0,1]
	v_max3_f32 v96, v96, v83, v100
	v_max3_f32 v97, v97, v102, v103
	v_pk_add_f32 v[104:105], v[120:121], v[228:229] op_sel_hi:[1,0] neg_lo:[0,1] neg_hi:[0,1]
	v_pk_add_f32 v[106:107], v[122:123], v[228:229] op_sel_hi:[1,0] neg_lo:[0,1] neg_hi:[0,1]
	v_max3_f32 v96, v96, v101, v84
	v_max3_f32 v97, v97, v86, v87
	v_pk_add_f32 v[88:89], v[136:137], v[228:229] op_sel_hi:[1,0] neg_lo:[0,1] neg_hi:[0,1]
	v_pk_add_f32 v[90:91], v[138:139], v[228:229] op_sel_hi:[1,0] neg_lo:[0,1] neg_hi:[0,1]
	v_max3_f32 v96, v96, v85, v104
	v_max3_f32 v97, v97, v106, v107
	v_pk_add_f32 v[108:109], v[124:125], v[228:229] op_sel_hi:[1,0] neg_lo:[0,1] neg_hi:[0,1]
	v_pk_add_f32 v[110:111], v[126:127], v[228:229] op_sel_hi:[1,0] neg_lo:[0,1] neg_hi:[0,1]
	v_max3_f32 v96, v96, v105, v88
	v_max3_f32 v97, v97, v90, v91
	v_pk_add_f32 v[92:93], v[140:141], v[228:229] op_sel_hi:[1,0] neg_lo:[0,1] neg_hi:[0,1]
	v_pk_add_f32 v[94:95], v[142:143], v[228:229] op_sel_hi:[1,0] neg_lo:[0,1] neg_hi:[0,1]
	v_max3_f32 v96, v96, v89, v108
	v_max3_f32 v97, v97, v110, v111
	v_max3_f32 v96, v96, v109, v92
	v_max3_f32 v97, v97, v94, v95
	v_max3_f32 v96, v96, v93, v97
	v_cmp_lt_f32_e32 vcc, s78, v96
	s_cmp_lg_u64 vcc, 0
	s_cselect_b64 s[48:49], -1, 0
	s_cbranch_vccnz .LBB0_1573

.LBB0_1570:
	v_mov_b32_e32 v97, v96
	s_nop 1
	v_permlane32_swap_b32_e32 v96, v97
	v_max_f32_e32 v97, v97, v97
	v_max_f32_e32 v96, v96, v96
	v_max_f32_e32 v96, v96, v97
	v_max_f32_e32 v96, v96, v96
	v_max_f32_e32 v97, 0, v96
	v_exp_f32_e64 v96, -v97
	s_and_saveexec_b64 s[44:45], s[8:9]
	ds_write_b32 v242, v96
	s_or_b64 exec, exec, s[44:45]
	v_sub_f32_e32 v80, v80, v97
	v_sub_f32_e32 v81, v81, v97
	v_sub_f32_e32 v98, v98, v97
	v_sub_f32_e32 v99, v99, v97
	v_sub_f32_e32 v100, v100, v97
	v_sub_f32_e32 v101, v101, v97
	v_sub_f32_e32 v102, v102, v97
	v_sub_f32_e32 v103, v103, v97
	v_sub_f32_e32 v104, v104, v97
	v_sub_f32_e32 v105, v105, v97
	v_sub_f32_e32 v106, v106, v97
	v_sub_f32_e32 v107, v107, v97
	v_sub_f32_e32 v108, v108, v97
	v_sub_f32_e32 v109, v109, v97
	v_sub_f32_e32 v110, v110, v97
	v_sub_f32_e32 v111, v111, v97
	v_sub_f32_e32 v14, v14, v97
	v_sub_f32_e32 v15, v15, v97
	v_sub_f32_e32 v82, v82, v97
	v_sub_f32_e32 v83, v83, v97
	v_sub_f32_e32 v84, v84, v97
	v_sub_f32_e32 v85, v85, v97
	v_sub_f32_e32 v86, v86, v97
	v_sub_f32_e32 v87, v87, v97
	v_sub_f32_e32 v88, v88, v97
	v_sub_f32_e32 v89, v89, v97
	v_sub_f32_e32 v90, v90, v97
	v_sub_f32_e32 v91, v91, v97
	v_sub_f32_e32 v92, v92, v97
	v_sub_f32_e32 v93, v93, v97
	v_sub_f32_e32 v94, v94, v97
	v_sub_f32_e32 v95, v95, v97
	v_add_f32_e32 v228, v228, v97
	v_mul_f32_e32 v250, v250, v96
	s_branch .LBB0_1533
.LBB0_1573:
	v_mov_b32_e32 v97, v96
	s_nop 1
	v_permlane32_swap_b32_e32 v96, v97
	v_max_f32_e32 v97, v97, v97
	v_max_f32_e32 v96, v96, v96
	v_max_f32_e32 v96, v96, v97
	v_max_f32_e32 v96, v96, v96
	v_max_f32_e32 v97, 0, v96
	v_exp_f32_e64 v96, -v97
	s_and_saveexec_b64 s[10:11], s[8:9]
	ds_write_b32 v242, v96
	s_or_b64 exec, exec, s[10:11]
	v_sub_f32_e32 v80, v80, v97
	v_sub_f32_e32 v81, v81, v97
	v_sub_f32_e32 v98, v98, v97
	v_sub_f32_e32 v99, v99, v97
	v_sub_f32_e32 v100, v100, v97
	v_sub_f32_e32 v101, v101, v97
	v_sub_f32_e32 v102, v102, v97
	v_sub_f32_e32 v103, v103, v97
	v_sub_f32_e32 v104, v104, v97
	v_sub_f32_e32 v105, v105, v97
	v_sub_f32_e32 v106, v106, v97
	v_sub_f32_e32 v107, v107, v97
	v_sub_f32_e32 v108, v108, v97
	v_sub_f32_e32 v109, v109, v97
	v_sub_f32_e32 v110, v110, v97
	v_sub_f32_e32 v111, v111, v97
	v_sub_f32_e32 v14, v14, v97
	v_sub_f32_e32 v15, v15, v97
	v_sub_f32_e32 v82, v82, v97
	v_sub_f32_e32 v83, v83, v97
	v_sub_f32_e32 v84, v84, v97
	v_sub_f32_e32 v85, v85, v97
	v_sub_f32_e32 v86, v86, v97
	v_sub_f32_e32 v87, v87, v97
	v_sub_f32_e32 v88, v88, v97
	v_sub_f32_e32 v89, v89, v97
	v_sub_f32_e32 v90, v90, v97
	v_sub_f32_e32 v91, v91, v97
	v_sub_f32_e32 v92, v92, v97
	v_sub_f32_e32 v93, v93, v97
	v_sub_f32_e32 v94, v94, v97
	v_sub_f32_e32 v95, v95, v97
	v_add_f32_e32 v228, v228, v97
	v_mul_f32_e32 v250, v250, v96
	s_branch .LBB0_1544
.LBB0_1576:
	v_add_u32_e32 v0, s90, v249
	ds_read_b64_tr_b16 v[2:3], v0 offset:24576
	ds_read_b64_tr_b16 v[4:5], v0 offset:25088
	s_waitcnt lgkmcnt(9)
	v_mfma_f32_32x32x16_bf16 v[112:127], v[204:207], v[172:175], 0
	v_add_f32_e32 v6, v96, v97
	v_add_f32_e32 v6, v98, v6
	v_add_f32_e32 v6, v99, v6
	v_add_f32_e32 v6, v100, v6
	v_add_f32_e32 v10, v101, v6
	v_cvt_pk_bf16_f32 v156, v96, v97
	v_cvt_pk_bf16_f32 v157, v98, v99
	ds_read_b64_tr_b16 v[6:7], v0 offset:28672
	ds_read_b64_tr_b16 v[8:9], v0 offset:29184
	v_add_f32_e32 v10, v102, v10
	v_add_f32_e32 v10, v103, v10
	v_add_f32_e32 v10, v104, v10
	v_add_f32_e32 v14, v105, v10
	v_cvt_pk_bf16_f32 v158, v100, v101
	v_cvt_pk_bf16_f32 v159, v102, v103
	s_waitcnt lgkmcnt(10)
	v_mfma_f32_32x32x16_bf16 v[128:143], v[200:203], v[172:175], 0
	ds_read_b64_tr_b16 v[10:11], v0 offset:25600
	ds_read_b64_tr_b16 v[12:13], v0 offset:26112
	s_waitcnt lgkmcnt(11)
	v_mfma_f32_32x32x16_bf16 v[112:127], v[196:199], v[168:171], v[112:127]
	v_add_f32_e32 v14, v106, v14
	v_add_f32_e32 v14, v107, v14
	v_add_f32_e32 v14, v108, v14
	v_add_f32_e32 v14, v109, v14
	v_cvt_pk_bf16_f32 v152, v104, v105
	v_cvt_pk_bf16_f32 v153, v106, v107
	ds_read_b64_tr_b16 v[172:173], v0 offset:29696
	ds_read_b64_tr_b16 v[174:175], v0 offset:30208
	v_add_f32_e32 v14, v110, v14
	v_add_f32_e32 v14, v111, v14
	v_add_f32_e32 v14, v80, v14
	v_add_f32_e32 v14, v81, v14
	v_cvt_pk_bf16_f32 v154, v108, v109
	v_cvt_pk_bf16_f32 v155, v110, v111
	s_waitcnt lgkmcnt(12)
	v_mfma_f32_32x32x16_bf16 v[128:143], v[192:195], v[168:171], v[128:143]
	ds_read_b64_tr_b16 v[168:169], v0 offset:26624
	ds_read_b64_tr_b16 v[170:171], v0 offset:27136
	s_waitcnt lgkmcnt(13)
	v_mfma_f32_32x32x16_bf16 v[112:127], v[188:191], v[164:167], v[112:127]
	v_add_f32_e32 v14, v82, v14
	v_add_f32_e32 v14, v83, v14
	v_add_f32_e32 v14, v84, v14
	v_add_f32_e32 v14, v85, v14
	v_cvt_pk_bf16_f32 v148, v80, v81
	v_cvt_pk_bf16_f32 v149, v82, v83
	ds_read_b64_tr_b16 v[188:189], v0 offset:30720
	ds_read_b64_tr_b16 v[190:191], v0 offset:31232
	v_add_f32_e32 v14, v86, v14
	v_add_f32_e32 v14, v87, v14
	v_add_f32_e32 v14, v88, v14
	v_add_f32_e32 v14, v89, v14
	v_cvt_pk_bf16_f32 v150, v84, v85
	v_cvt_pk_bf16_f32 v151, v86, v87
	s_waitcnt lgkmcnt(14)
	v_mfma_f32_32x32x16_bf16 v[128:143], v[184:187], v[164:167], v[128:143]
	ds_read_b64_tr_b16 v[164:165], v0 offset:27648
	ds_read_b64_tr_b16 v[166:167], v0 offset:28160
	s_waitcnt lgkmcnt(14)
; __device__ __forceinline__ void biasd(f32x16&p0,f32x16&p1,const __attribute__((address_space(3))) float*lut,int base){
;   #pragma unroll
;   for(int r=0;r<16;++r){ const int d0=base-((r&3)+8*(r>>2)); unsigned i0=(unsigned)d0; i0=i0>127u?127u:i0; unsigned i1=(unsigned)(d0-32); i1=i1>127u?127u:i1; p0[r]+=lut[i0]; p1[r]+=lut[i1];
;     if((r&3)==3){ asm volatile("":"+v"(p0),"+v"(p1)); __builtin_amdgcn_sched_barrier(0); } }
; }
	v_mfma_f32_32x32x16_bf16 v[112:127], v[180:183], v[160:163], v[112:127]
	v_add_f32_e32 v14, v90, v14
	v_add_f32_e32 v14, v91, v14
	v_add_f32_e32 v14, v92, v14
	v_add_f32_e32 v14, v93, v14
	v_cvt_pk_bf16_f32 v144, v88, v89
	v_cvt_pk_bf16_f32 v145, v90, v91
	ds_read_b64_tr_b16 v[180:181], v0 offset:31744
	ds_read_b64_tr_b16 v[182:183], v0 offset:32256
	v_add_f32_e32 v14, v94, v14
	v_add_f32_e32 v14, v95, v14
	v_add_f32_e32 v96, 0, v14
	v_cvt_pk_bf16_f32 v146, v92, v93
	v_cvt_pk_bf16_f32 v147, v94, v95
	v_mfma_f32_32x32x16_bf16 v[128:143], v[176:179], v[160:163], v[128:143]
	v_sub_u32_e32 v86, v245, v244
	v_add_u32_e32 v80, 0xffffff3f, v86
	v_min_u32_e32 v80, 0x7f, v80
	v_lshl_add_u32 v82, v80, 2, s85
	v_add_u32_e32 v80, 0xffffff3e, v86
	v_add_u32_e32 v14, 0xffffff40, v86
	v_add_u32_e32 v15, 0xffffff20, v86
	v_add_u32_e32 v81, 0xffffff1f, v86
	v_min_u32_e32 v80, 0x7f, v80
	v_add_u32_e32 v83, 0xffffff1e, v86
	v_add_u32_e32 v85, 0xffffff1d, v86
	v_min_u32_e32 v14, 0x7f, v14
	v_min_u32_e32 v15, 0x7f, v15
	v_min_u32_e32 v81, 0x7f, v81
	v_min_u32_e32 v83, 0x7f, v83
	v_lshl_add_u32 v84, v80, 2, s85
	v_add_u32_e32 v80, 0xffffff3d, v86
	v_min_u32_e32 v85, 0x7f, v85
	v_lshl_add_u32 v14, v14, 2, s85
	v_lshl_add_u32 v15, v15, 2, s85
	v_lshl_add_u32 v81, v81, 2, s85
	v_lshl_add_u32 v83, v83, 2, s85
	v_min_u32_e32 v80, 0x7f, v80
	v_lshl_add_u32 v85, v85, 2, s85
	v_lshl_add_u32 v87, v80, 2, s85
	ds_read_b32 v14, v14
	ds_read_b32 v80, v15
	ds_read_b32 v15, v82
	ds_read_b32 v81, v81
	ds_read_b32 v82, v84
	ds_read_b32 v84, v83
	ds_read_b32 v83, v87
	ds_read_b32 v85, v85
	s_waitcnt lgkmcnt(5)
	v_pk_add_f32 v[112:113], v[112:113], v[14:15]
	s_waitcnt lgkmcnt(4)
	v_pk_add_f32 v[128:129], v[128:129], v[80:81]
	s_waitcnt lgkmcnt(1)
	v_pk_add_f32 v[114:115], v[114:115], v[82:83]
	s_waitcnt lgkmcnt(0)
	v_pk_add_f32 v[130:131], v[130:131], v[84:85]
	s_nop 0
	v_add_u32_e32 v80, 0xffffff37, v86
	v_min_u32_e32 v80, 0x7f, v80
	v_lshl_add_u32 v82, v80, 2, s85
	v_add_u32_e32 v80, 0xffffff36, v86
	v_add_u32_e32 v14, 0xffffff38, v86
	v_add_u32_e32 v15, 0xffffff18, v86
	v_add_u32_e32 v81, 0xffffff17, v86
	v_min_u32_e32 v80, 0x7f, v80
	v_add_u32_e32 v83, 0xffffff16, v86
	v_add_u32_e32 v85, 0xffffff15, v86
	v_min_u32_e32 v14, 0x7f, v14
	v_min_u32_e32 v15, 0x7f, v15
	v_min_u32_e32 v81, 0x7f, v81
	v_min_u32_e32 v83, 0x7f, v83
	v_lshl_add_u32 v84, v80, 2, s85
	v_add_u32_e32 v80, 0xffffff35, v86
	v_min_u32_e32 v85, 0x7f, v85
	v_lshl_add_u32 v14, v14, 2, s85
	v_lshl_add_u32 v15, v15, 2, s85
	v_lshl_add_u32 v81, v81, 2, s85
	v_lshl_add_u32 v83, v83, 2, s85
	v_min_u32_e32 v80, 0x7f, v80
	v_lshl_add_u32 v85, v85, 2, s85
	v_lshl_add_u32 v87, v80, 2, s85
	ds_read_b32 v14, v14
	ds_read_b32 v80, v15
	ds_read_b32 v15, v82
	ds_read_b32 v81, v81
	ds_read_b32 v82, v84
	ds_read_b32 v84, v83
	ds_read_b32 v83, v87
	ds_read_b32 v85, v85
	s_waitcnt lgkmcnt(5)
	v_pk_add_f32 v[116:117], v[14:15], v[116:117]
	s_waitcnt lgkmcnt(4)
	v_pk_add_f32 v[132:133], v[132:133], v[80:81]
	s_waitcnt lgkmcnt(1)
	v_pk_add_f32 v[118:119], v[118:119], v[82:83]
	s_waitcnt lgkmcnt(0)
	v_pk_add_f32 v[134:135], v[134:135], v[84:85]
	s_nop 0
	v_add_u32_e32 v80, 0xffffff2f, v86
	v_min_u32_e32 v80, 0x7f, v80
	v_lshl_add_u32 v82, v80, 2, s85
	v_add_u32_e32 v80, 0xffffff2e, v86
	v_add_u32_e32 v14, 0xffffff30, v86
	v_add_u32_e32 v15, 0xffffff10, v86
	v_add_u32_e32 v81, 0xffffff0f, v86
	v_min_u32_e32 v80, 0x7f, v80
	v_add_u32_e32 v83, 0xffffff0e, v86
	v_add_u32_e32 v85, 0xffffff0d, v86
	v_min_u32_e32 v14, 0x7f, v14
	v_min_u32_e32 v15, 0x7f, v15
	v_min_u32_e32 v81, 0x7f, v81
	v_min_u32_e32 v83, 0x7f, v83
	v_lshl_add_u32 v84, v80, 2, s85
	v_add_u32_e32 v80, 0xffffff2d, v86
	v_min_u32_e32 v85, 0x7f, v85
	v_lshl_add_u32 v14, v14, 2, s85
	v_lshl_add_u32 v15, v15, 2, s85
	v_lshl_add_u32 v81, v81, 2, s85
	v_lshl_add_u32 v83, v83, 2, s85
	v_min_u32_e32 v80, 0x7f, v80
	v_lshl_add_u32 v85, v85, 2, s85
	v_lshl_add_u32 v87, v80, 2, s85
	ds_read_b32 v14, v14
	ds_read_b32 v80, v15
	ds_read_b32 v15, v82
	ds_read_b32 v81, v81
	ds_read_b32 v82, v84
	ds_read_b32 v84, v83
	ds_read_b32 v83, v87
	ds_read_b32 v85, v85
	s_waitcnt lgkmcnt(5)
	v_pk_add_f32 v[120:121], v[14:15], v[120:121]
	s_waitcnt lgkmcnt(4)
	v_pk_add_f32 v[136:137], v[136:137], v[80:81]
	s_waitcnt lgkmcnt(1)
	v_pk_add_f32 v[122:123], v[122:123], v[82:83]
	s_waitcnt lgkmcnt(0)
	v_pk_add_f32 v[138:139], v[138:139], v[84:85]
	s_nop 0
	v_add_u32_e32 v80, 0xffffff27, v86
	v_min_u32_e32 v80, 0x7f, v80
	v_lshl_add_u32 v82, v80, 2, s85
	v_add_u32_e32 v80, 0xffffff26, v86
	v_add_u32_e32 v14, 0xffffff28, v86
	v_add_u32_e32 v15, 0xffffff08, v86
	v_add_u32_e32 v81, 0xffffff07, v86
	v_min_u32_e32 v80, 0x7f, v80
	v_add_u32_e32 v83, 0xffffff06, v86
	v_add_u32_e32 v85, 0xffffff05, v86
	v_min_u32_e32 v14, 0x7f, v14
	v_min_u32_e32 v15, 0x7f, v15
	v_min_u32_e32 v81, 0x7f, v81
	v_min_u32_e32 v83, 0x7f, v83
	v_lshl_add_u32 v84, v80, 2, s85
	v_add_u32_e32 v80, 0xffffff25, v86
	v_min_u32_e32 v85, 0x7f, v85
	v_lshl_add_u32 v14, v14, 2, s85
	v_lshl_add_u32 v15, v15, 2, s85
	v_lshl_add_u32 v81, v81, 2, s85
	v_lshl_add_u32 v83, v83, 2, s85
	v_min_u32_e32 v80, 0x7f, v80
	v_lshl_add_u32 v85, v85, 2, s85
	v_lshl_add_u32 v86, v80, 2, s85
	ds_read_b32 v14, v14
	ds_read_b32 v80, v15
	ds_read_b32 v15, v82
	ds_read_b32 v81, v81
	ds_read_b32 v82, v84
	ds_read_b32 v84, v83
	ds_read_b32 v83, v86
	ds_read_b32 v85, v85
	s_waitcnt lgkmcnt(5)
	v_pk_add_f32 v[124:125], v[14:15], v[124:125]
	s_waitcnt lgkmcnt(4)
	v_pk_add_f32 v[140:141], v[140:141], v[80:81]
	s_waitcnt lgkmcnt(1)
	v_pk_add_f32 v[126:127], v[126:127], v[82:83]
	s_waitcnt lgkmcnt(0)
; __device__ __forceinline__ void cmask(f32x16&p0,f32x16&p1,int jb,int qrel,int hi){
;   const float NEG=-INFINITY; int kb=64*jb+4*hi;
;   #pragma unroll
;   for(int r=0;r<16;++r){int kv=kb+(r&3)+8*(r>>2); if(kv>qrel)p0[r]=NEG; if(kv+32>qrel)p1[r]=NEG;}
; }
	v_pk_add_f32 v[142:143], v[142:143], v[84:85]
	s_nop 0
	v_or_b32_e32 v14, 0xe0, v244
	v_or_b32_e32 v15, 0xc0, v244
	v_cmp_le_u32_e32 vcc, v14, v245
	v_or_b32_e32 v82, 0xc2, v244
	v_or_b32_e32 v83, 0xe2, v244
	v_cndmask_b32_e32 v14, v234, v128, vcc
	v_cmp_lt_u32_e32 vcc, v15, v245
	v_or_b32_e32 v85, 0xe3, v244
	v_or_b32_e32 v86, 0xc8, v244
	v_cndmask_b32_e32 v81, v234, v113, vcc
	v_cmp_le_u32_e32 vcc, v15, v245
	v_or_b32_e32 v15, 0xe1, v244
	v_or_b32_e32 v87, 0xe8, v244
	v_cndmask_b32_e32 v80, v234, v112, vcc
	v_cmp_le_u32_e32 vcc, v15, v245
	v_or_b32_e32 v89, 0xe9, v244
	v_or_b32_e32 v90, 0xca, v244
	v_cndmask_b32_e32 v15, v234, v129, vcc
	v_cmp_le_u32_e32 vcc, v82, v245
	v_or_b32_e32 v91, 0xea, v244
	v_or_b32_e32 v93, 0xeb, v244
	v_cndmask_b32_e32 v82, v234, v114, vcc
	v_cmp_le_u32_e32 vcc, v83, v245
	v_or_b32_e32 v83, 0xc3, v244
	v_or_b32_e32 v94, 0xd0, v244
	v_cndmask_b32_e32 v84, v234, v130, vcc
	v_cmp_le_u32_e32 vcc, v83, v245
	v_or_b32_e32 v95, 0xf0, v244
	v_or_b32_e32 v97, 0xf1, v244
	v_cndmask_b32_e32 v83, v234, v115, vcc
	v_cmp_le_u32_e32 vcc, v85, v245
	v_pk_add_f32 v[80:81], v[80:81], v[228:229] op_sel_hi:[1,0] neg_lo:[0,1] neg_hi:[0,1]
	v_pk_add_f32 v[14:15], v[14:15], v[228:229] op_sel_hi:[1,0] neg_lo:[0,1] neg_hi:[0,1]
	v_cndmask_b32_e32 v85, v234, v131, vcc
	v_cmp_le_u32_e32 vcc, v86, v245
	v_pk_add_f32 v[98:99], v[82:83], v[228:229] op_sel_hi:[1,0] neg_lo:[0,1] neg_hi:[0,1]
	v_pk_add_f32 v[82:83], v[84:85], v[228:229] op_sel_hi:[1,0] neg_lo:[0,1] neg_hi:[0,1]
	v_cndmask_b32_e32 v86, v234, v116, vcc
	v_cmp_le_u32_e32 vcc, v87, v245
	v_or_b32_e32 v87, 0xc9, v244
	s_nop 0
	v_cndmask_b32_e32 v88, v234, v132, vcc
	v_cmp_le_u32_e32 vcc, v87, v245
	s_nop 1
	v_cndmask_b32_e32 v87, v234, v117, vcc
	v_cmp_le_u32_e32 vcc, v89, v245
	v_pk_add_f32 v[100:101], v[86:87], v[228:229] op_sel_hi:[1,0] neg_lo:[0,1] neg_hi:[0,1]
	s_nop 0
	v_cndmask_b32_e32 v89, v234, v133, vcc
	v_cmp_le_u32_e32 vcc, v90, v245
	v_pk_add_f32 v[84:85], v[88:89], v[228:229] op_sel_hi:[1,0] neg_lo:[0,1] neg_hi:[0,1]
	s_nop 0
	v_cndmask_b32_e32 v90, v234, v118, vcc
	v_cmp_le_u32_e32 vcc, v91, v245
	v_or_b32_e32 v91, 0xcb, v244
	s_nop 0
	v_cndmask_b32_e32 v92, v234, v134, vcc
	v_cmp_le_u32_e32 vcc, v91, v245
	s_nop 1
	v_cndmask_b32_e32 v91, v234, v119, vcc
	v_cmp_le_u32_e32 vcc, v93, v245
	v_pk_add_f32 v[102:103], v[90:91], v[228:229] op_sel_hi:[1,0] neg_lo:[0,1] neg_hi:[0,1]
	s_nop 0
	v_cndmask_b32_e32 v93, v234, v135, vcc
	v_cmp_le_u32_e32 vcc, v94, v245
	v_pk_add_f32 v[86:87], v[92:93], v[228:229] op_sel_hi:[1,0] neg_lo:[0,1] neg_hi:[0,1]
	s_nop 0
	v_cndmask_b32_e32 v94, v234, v120, vcc
	v_cmp_le_u32_e32 vcc, v95, v245
	v_or_b32_e32 v95, 0xd1, v244
	s_nop 0
	v_cndmask_b32_e32 v106, v234, v136, vcc
	v_cmp_le_u32_e32 vcc, v95, v245
	s_nop 1
	v_cndmask_b32_e32 v95, v234, v121, vcc
	v_cmp_le_u32_e32 vcc, v97, v245
	v_or_b32_e32 v97, 0xd2, v244
	v_pk_add_f32 v[104:105], v[94:95], v[228:229] op_sel_hi:[1,0] neg_lo:[0,1] neg_hi:[0,1]
	v_cndmask_b32_e32 v107, v234, v137, vcc
	v_cmp_le_u32_e32 vcc, v97, v245
	v_or_b32_e32 v97, 0xf2, v244
	v_pk_add_f32 v[88:89], v[106:107], v[228:229] op_sel_hi:[1,0] neg_lo:[0,1] neg_hi:[0,1]
	v_cndmask_b32_e32 v108, v234, v122, vcc
	v_cmp_le_u32_e32 vcc, v97, v245
	v_or_b32_e32 v97, 0xd3, v244
	s_nop 0
	v_cndmask_b32_e32 v110, v234, v138, vcc
	v_cmp_le_u32_e32 vcc, v97, v245
	v_or_b32_e32 v97, 0xf3, v244
	s_nop 0
	v_cndmask_b32_e32 v109, v234, v123, vcc
	v_cmp_le_u32_e32 vcc, v97, v245
	v_or_b32_e32 v97, 0xd8, v244
	v_pk_add_f32 v[106:107], v[108:109], v[228:229] op_sel_hi:[1,0] neg_lo:[0,1] neg_hi:[0,1]
	v_cndmask_b32_e32 v111, v234, v139, vcc
	v_cmp_le_u32_e32 vcc, v97, v245
	v_or_b32_e32 v97, 0xf8, v244
	v_pk_add_f32 v[90:91], v[110:111], v[228:229] op_sel_hi:[1,0] neg_lo:[0,1] neg_hi:[0,1]
	v_cndmask_b32_e32 v112, v234, v124, vcc
	v_cmp_le_u32_e32 vcc, v97, v245
	v_or_b32_e32 v97, 0xd9, v244
	s_nop 0
	v_cndmask_b32_e32 v114, v234, v140, vcc
	v_cmp_le_u32_e32 vcc, v97, v245
	v_or_b32_e32 v97, 0xf9, v244
	s_nop 0
	v_cndmask_b32_e32 v113, v234, v125, vcc
	v_cmp_le_u32_e32 vcc, v97, v245
	v_or_b32_e32 v97, 0xda, v244
	v_pk_add_f32 v[108:109], v[112:113], v[228:229] op_sel_hi:[1,0] neg_lo:[0,1] neg_hi:[0,1]
	v_cndmask_b32_e32 v115, v234, v141, vcc
	v_cmp_le_u32_e32 vcc, v97, v245
	v_or_b32_e32 v97, 0xfa, v244
	v_max3_f32 v112, v98, v99, v15
	v_cndmask_b32_e32 v116, v234, v126, vcc
	v_cmp_le_u32_e32 vcc, v97, v245
	v_or_b32_e32 v97, 0xdb, v244
	v_max3_f32 v112, v112, v102, v103
	v_cndmask_b32_e32 v118, v234, v142, vcc
	v_cmp_le_u32_e32 vcc, v97, v245
	v_or_b32_e32 v97, 0xfb, v244
	v_max3_f32 v112, v112, v86, v87
	v_cndmask_b32_e32 v117, v234, v127, vcc
	v_cmp_le_u32_e32 vcc, v97, v245
	v_max_f32_e32 v97, v80, v81
	v_max3_f32 v97, v97, v14, v82
	v_max3_f32 v97, v97, v83, v100
	v_max3_f32 v97, v97, v101, v84
	v_max3_f32 v97, v97, v85, v104
	v_max3_f32 v112, v112, v106, v107
	v_cndmask_b32_e32 v119, v234, v143, vcc
	v_pk_add_f32 v[110:111], v[116:117], v[228:229] op_sel_hi:[1,0] neg_lo:[0,1] neg_hi:[0,1]
	v_max3_f32 v97, v97, v105, v88
	v_max3_f32 v112, v112, v90, v91
	v_pk_add_f32 v[92:93], v[114:115], v[228:229] op_sel_hi:[1,0] neg_lo:[0,1] neg_hi:[0,1]
	v_pk_add_f32 v[94:95], v[118:119], v[228:229] op_sel_hi:[1,0] neg_lo:[0,1] neg_hi:[0,1]
	v_max3_f32 v97, v97, v89, v108
	v_max3_f32 v112, v112, v110, v111
	v_max3_f32 v97, v97, v109, v92
	v_max3_f32 v113, v112, v94, v95
	v_add_f32_e32 v112, v250, v96
	v_max3_f32 v96, v97, v93, v113
	v_cmp_lt_f32_e32 vcc, s78, v96
	s_cmp_lg_u64 vcc, 0
	s_cselect_b64 s[8:9], -1, 0
	s_cbranch_vccnz .LBB0_1581

.LBB0_1581:
	v_mov_b32_e32 v97, v96
	s_nop 1
	v_permlane32_swap_b32_e32 v96, v97
	v_max_f32_e32 v97, v97, v97
	v_max_f32_e32 v96, v96, v96
	v_max_f32_e32 v96, v96, v97
	v_max_f32_e32 v96, v96, v96
	v_max_f32_e32 v97, 0, v96
	v_exp_f32_e64 v96, -v97
	v_cmp_gt_u32_e32 vcc, 32, v236
	s_and_saveexec_b64 s[10:11], vcc
	ds_write_b32 v242, v96
	s_or_b64 exec, exec, s[10:11]
	v_sub_f32_e32 v80, v80, v97
	v_sub_f32_e32 v81, v81, v97
	v_sub_f32_e32 v98, v98, v97
	v_sub_f32_e32 v99, v99, v97
	v_sub_f32_e32 v100, v100, v97
	v_sub_f32_e32 v101, v101, v97
	v_sub_f32_e32 v102, v102, v97
	v_sub_f32_e32 v103, v103, v97
	v_sub_f32_e32 v104, v104, v97
	v_sub_f32_e32 v105, v105, v97
	v_sub_f32_e32 v106, v106, v97
	v_sub_f32_e32 v107, v107, v97
	v_sub_f32_e32 v108, v108, v97
	v_sub_f32_e32 v109, v109, v97
	v_sub_f32_e32 v110, v110, v97
	v_sub_f32_e32 v111, v111, v97
	v_sub_f32_e32 v14, v14, v97
	v_sub_f32_e32 v15, v15, v97
	v_sub_f32_e32 v82, v82, v97
	v_sub_f32_e32 v83, v83, v97
	v_sub_f32_e32 v84, v84, v97
	v_sub_f32_e32 v85, v85, v97
	v_sub_f32_e32 v86, v86, v97
	v_sub_f32_e32 v87, v87, v97
	v_sub_f32_e32 v88, v88, v97
	v_sub_f32_e32 v89, v89, v97
	v_sub_f32_e32 v90, v90, v97
	v_sub_f32_e32 v91, v91, v97
	v_sub_f32_e32 v92, v92, v97
	v_sub_f32_e32 v93, v93, v97
	v_sub_f32_e32 v94, v94, v97
	v_sub_f32_e32 v95, v95, v97
	v_mul_f32_e32 v112, v112, v96
	s_branch .LBB0_1577
